# final_norm_output_stores_nt
# baseline (speedup 1.0000x reference)
.LBB0_3038:
	s_or_b64 exec, exec, s[28:29]
	s_waitcnt lgkmcnt(0)
	s_barrier
	s_load_dwordx2 s[0:1], s[80:81], 0x108
	v_and_b32_e32 v154, 64, v164
	s_waitcnt lgkmcnt(0)
	global_load_dwordx4 v[88:91], v144, s[0:1] offset:16
	global_load_dwordx4 v[92:95], v144, s[0:1]
	global_load_dwordx4 v[76:79], v144, s[0:1] offset:2064
	global_load_dwordx4 v[80:83], v144, s[0:1] offset:2048
	v_add_u32_e32 v171, 64, v154
	v_xor_b32_e32 v154, 1, v164
	v_cmp_lt_i32_e32 vcc, v154, v171
	s_waitcnt vmcnt(5)
	v_and_b32_e32 v163, 0xffff0000, v140
	v_and_b32_e32 v161, 0xffff0000, v141
	v_cndmask_b32_e32 v154, v164, v154, vcc
	v_lshlrev_b32_e32 v166, 2, v154
	v_lshlrev_b32_e32 v162, 16, v140
	v_lshlrev_b32_e32 v160, 16, v141
	v_lshlrev_b32_e32 v158, 16, v142
	v_and_b32_e32 v159, 0xffff0000, v142
	v_lshlrev_b32_e32 v156, 16, v143
	v_and_b32_e32 v157, 0xffff0000, v143
	s_waitcnt vmcnt(4)
	v_lshlrev_b32_e32 v154, 16, v136
	v_and_b32_e32 v155, 0xffff0000, v136
	v_lshlrev_b32_e32 v142, 16, v137
	v_and_b32_e32 v143, 0xffff0000, v137
	v_lshlrev_b32_e32 v140, 16, v138
	v_and_b32_e32 v141, 0xffff0000, v138
	v_lshlrev_b32_e32 v136, 16, v139
	v_and_b32_e32 v137, 0xffff0000, v139
	v_mul_f32_e32 v138, v163, v163
	v_mul_f32_e32 v139, v161, v161
	v_fmac_f32_e32 v138, v162, v162
	v_fmac_f32_e32 v139, v160, v160
	v_add_f32_e32 v138, v138, v139
	v_mul_f32_e32 v139, v159, v159
	v_mul_f32_e32 v167, v157, v157
	v_fmac_f32_e32 v139, v158, v158
	v_fmac_f32_e32 v167, v156, v156
	v_add_f32_e32 v139, v139, v167
	v_add_f32_e32 v138, v138, v139
	v_mul_f32_e32 v139, v155, v155
	v_mul_f32_e32 v167, v143, v143
	v_fmac_f32_e32 v139, v154, v154
	v_fmac_f32_e32 v167, v142, v142
	v_add_f32_e32 v139, v139, v167
	v_add_f32_e32 v138, v139, v138
	v_mul_f32_e32 v139, v141, v141
	v_mul_f32_e32 v167, v137, v137
	v_fmac_f32_e32 v139, v140, v140
	v_fmac_f32_e32 v167, v136, v136
	v_add_f32_e32 v139, v139, v167
	v_add_f32_e32 v138, v139, v138
	ds_bpermute_b32 v139, v166, v138
	v_xor_b32_e32 v167, 2, v164
	v_cmp_lt_i32_e32 vcc, v167, v171
	v_xor_b32_e32 v168, 4, v164
	v_xor_b32_e32 v169, 8, v164
	v_cndmask_b32_e32 v167, v164, v167, vcc
	v_lshlrev_b32_e32 v167, 2, v167
	s_waitcnt lgkmcnt(0)
	v_add_f32_e32 v138, v138, v139
	ds_bpermute_b32 v139, v167, v138
	v_cmp_lt_i32_e32 vcc, v168, v171
	v_xor_b32_e32 v170, 16, v164
	v_xor_b32_e32 v172, 32, v164
	v_cndmask_b32_e32 v168, v164, v168, vcc
	v_lshlrev_b32_e32 v168, 2, v168
	s_waitcnt lgkmcnt(0)
	v_add_f32_e32 v138, v138, v139
	ds_bpermute_b32 v139, v168, v138
	v_cmp_lt_i32_e32 vcc, v169, v171
	s_waitcnt lgkmcnt(0)
	v_add_f32_e32 v138, v138, v139
	v_cndmask_b32_e32 v169, v164, v169, vcc
	v_lshlrev_b32_e32 v169, 2, v169
	ds_bpermute_b32 v139, v169, v138
	v_cmp_lt_i32_e32 vcc, v170, v171
	s_waitcnt lgkmcnt(0)
	v_add_f32_e32 v138, v138, v139
	v_cndmask_b32_e32 v170, v164, v170, vcc
	v_lshlrev_b32_e32 v170, 2, v170
	ds_bpermute_b32 v139, v170, v138
	v_cmp_lt_i32_e32 vcc, v172, v171
	s_waitcnt lgkmcnt(0)
	v_add_f32_e32 v138, v138, v139
	v_cndmask_b32_e32 v171, v164, v172, vcc
	v_lshlrev_b32_e32 v171, 2, v171
	ds_bpermute_b32 v139, v171, v138
	s_andn2_b64 vcc, exec, s[68:69]
	s_cbranch_vccnz .LBB0_3040
	s_waitcnt lgkmcnt(0)
	v_add_f32_e32 v138, v138, v139
	v_fmamk_f32 v138, v138, 0x3a800000, v165
	v_rsq_f32_e32 v138, v138
	s_lshl_b64 s[0:1], s[26:27], 12
	v_pk_mul_f32 v[172:173], v[162:163], v[138:139] op_sel_hi:[1,0]
	v_pk_mul_f32 v[160:161], v[160:161], v[138:139] op_sel_hi:[1,0]
	v_pk_mul_f32 v[156:157], v[156:157], v[138:139] op_sel_hi:[1,0]
	s_waitcnt vmcnt(2)
	v_pk_mul_f32 v[162:163], v[94:95], v[160:161]
	v_pk_mul_f32 v[160:161], v[92:93], v[172:173]
	v_lshl_add_u64 v[172:173], v[148:149], 0, s[0:1]
	global_store_dwordx4 v[172:173], v[160:163], off nt
	v_pk_mul_f32 v[154:155], v[154:155], v[138:139] op_sel_hi:[1,0]
	v_pk_mul_f32 v[142:143], v[142:143], v[138:139] op_sel_hi:[1,0]
	v_pk_mul_f32 v[160:161], v[158:159], v[138:139] op_sel_hi:[1,0]
	v_pk_mul_f32 v[158:159], v[90:91], v[156:157]
	v_pk_mul_f32 v[156:157], v[88:89], v[160:161]
	v_pk_mul_f32 v[140:141], v[140:141], v[138:139] op_sel_hi:[1,0]
	v_pk_mul_f32 v[136:137], v[136:137], v[138:139] op_sel_hi:[1,0]
	global_store_dwordx4 v[172:173], v[156:159], off offset:16 nt
	s_waitcnt vmcnt(2)
	v_pk_mul_f32 v[154:155], v[80:81], v[154:155]
	v_pk_mul_f32 v[138:139], v[78:79], v[136:137]
	v_pk_mul_f32 v[156:157], v[82:83], v[142:143]
	v_pk_mul_f32 v[136:137], v[76:77], v[140:141]
	global_store_dwordx4 v[172:173], v[154:157], off offset:2048 nt
	global_store_dwordx4 v[172:173], v[136:139], off offset:2064 nt
.LBB0_3040:
	s_nop 0
	v_and_b32_e32 v155, 0xffff0000, v132
	v_and_b32_e32 v143, 0xffff0000, v133
	v_lshlrev_b32_e32 v154, 16, v132
	v_lshlrev_b32_e32 v142, 16, v133
	v_lshlrev_b32_e32 v140, 16, v134
	v_and_b32_e32 v141, 0xffff0000, v134
	v_lshlrev_b32_e32 v138, 16, v135
	s_waitcnt lgkmcnt(0)
	v_and_b32_e32 v139, 0xffff0000, v135
	v_lshlrev_b32_e32 v136, 16, v128
	v_and_b32_e32 v137, 0xffff0000, v128
	v_lshlrev_b32_e32 v134, 16, v129
	v_and_b32_e32 v135, 0xffff0000, v129
	v_lshlrev_b32_e32 v132, 16, v130
	v_and_b32_e32 v133, 0xffff0000, v130
	v_lshlrev_b32_e32 v128, 16, v131
	v_and_b32_e32 v129, 0xffff0000, v131
	v_mul_f32_e32 v130, v155, v155
	v_mul_f32_e32 v131, v143, v143
	v_fmac_f32_e32 v130, v154, v154
	v_fmac_f32_e32 v131, v142, v142
	v_add_f32_e32 v130, v130, v131
	v_mul_f32_e32 v131, v141, v141
	v_mul_f32_e32 v156, v139, v139
	v_fmac_f32_e32 v131, v140, v140
	v_fmac_f32_e32 v156, v138, v138
	v_add_f32_e32 v131, v131, v156
	v_add_f32_e32 v130, v130, v131
	v_mul_f32_e32 v131, v137, v137
	v_mul_f32_e32 v156, v135, v135
	v_fmac_f32_e32 v131, v136, v136
	v_fmac_f32_e32 v156, v134, v134
	v_add_f32_e32 v131, v131, v156
	v_add_f32_e32 v130, v131, v130
	v_mul_f32_e32 v131, v133, v133
	v_mul_f32_e32 v156, v129, v129
	v_fmac_f32_e32 v131, v132, v132
	v_fmac_f32_e32 v156, v128, v128
	v_add_f32_e32 v131, v131, v156
	v_add_f32_e32 v130, v131, v130
	ds_bpermute_b32 v131, v166, v130
	s_andn2_b64 vcc, exec, s[66:67]
	s_waitcnt lgkmcnt(0)
	v_add_f32_e32 v130, v130, v131
	ds_bpermute_b32 v131, v167, v130
	s_waitcnt lgkmcnt(0)
	v_add_f32_e32 v130, v130, v131
	ds_bpermute_b32 v131, v168, v130
	s_waitcnt lgkmcnt(0)
	v_add_f32_e32 v130, v130, v131
	ds_bpermute_b32 v131, v169, v130
	s_waitcnt lgkmcnt(0)
	v_add_f32_e32 v130, v130, v131
	ds_bpermute_b32 v131, v170, v130
	s_waitcnt lgkmcnt(0)
	v_add_f32_e32 v130, v130, v131
	ds_bpermute_b32 v131, v171, v130
	s_cbranch_vccnz .LBB0_3042
	s_waitcnt lgkmcnt(0)
	v_add_f32_e32 v130, v130, v131
	v_fmamk_f32 v130, v130, 0x3a800000, v165
	v_rsq_f32_e32 v130, v130
	s_lshl_b64 s[0:1], s[24:25], 12
	v_pk_mul_f32 v[154:155], v[154:155], v[130:131] op_sel_hi:[1,0]
	v_pk_mul_f32 v[142:143], v[142:143], v[130:131] op_sel_hi:[1,0]
	s_waitcnt vmcnt(2)
	v_pk_mul_f32 v[154:155], v[92:93], v[154:155]
	v_pk_mul_f32 v[156:157], v[94:95], v[142:143]
	v_lshl_add_u64 v[142:143], v[148:149], 0, s[0:1]
	global_store_dwordx4 v[142:143], v[154:157], off nt
	v_pk_mul_f32 v[138:139], v[138:139], v[130:131] op_sel_hi:[1,0]
	v_pk_mul_f32 v[134:135], v[134:135], v[130:131] op_sel_hi:[1,0]
	v_pk_mul_f32 v[154:155], v[140:141], v[130:131] op_sel_hi:[1,0]
	v_pk_mul_f32 v[140:141], v[90:91], v[138:139]
	v_pk_mul_f32 v[138:139], v[88:89], v[154:155]
	global_store_dwordx4 v[142:143], v[138:141], off offset:16 nt
	v_pk_mul_f32 v[132:133], v[132:133], v[130:131] op_sel_hi:[1,0]
	v_pk_mul_f32 v[128:129], v[128:129], v[130:131] op_sel_hi:[1,0]
	v_pk_mul_f32 v[138:139], v[136:137], v[130:131] op_sel_hi:[1,0]
	s_waitcnt vmcnt(2)
	v_pk_mul_f32 v[136:137], v[82:83], v[134:135]
	v_pk_mul_f32 v[134:135], v[80:81], v[138:139]
	v_pk_mul_f32 v[130:131], v[78:79], v[128:129]
	v_pk_mul_f32 v[128:129], v[76:77], v[132:133]
	global_store_dwordx4 v[142:143], v[134:137], off offset:2048 nt
	global_store_dwordx4 v[142:143], v[128:131], off offset:2064 nt
.LBB0_3042:
	s_nop 0
	v_and_b32_e32 v137, 0xffff0000, v124
	v_and_b32_e32 v135, 0xffff0000, v125
	v_lshlrev_b32_e32 v136, 16, v124
	v_lshlrev_b32_e32 v134, 16, v125
	v_lshlrev_b32_e32 v132, 16, v126
	v_and_b32_e32 v133, 0xffff0000, v126
	v_lshlrev_b32_e32 v130, 16, v127
	s_waitcnt lgkmcnt(0)
	v_and_b32_e32 v131, 0xffff0000, v127
	v_lshlrev_b32_e32 v128, 16, v120
	v_and_b32_e32 v129, 0xffff0000, v120
	v_lshlrev_b32_e32 v126, 16, v121
	v_and_b32_e32 v127, 0xffff0000, v121
	v_lshlrev_b32_e32 v124, 16, v122
	v_and_b32_e32 v125, 0xffff0000, v122
	v_lshlrev_b32_e32 v120, 16, v123
	v_and_b32_e32 v121, 0xffff0000, v123
	v_mul_f32_e32 v122, v137, v137
	v_mul_f32_e32 v123, v135, v135
	v_fmac_f32_e32 v122, v136, v136
	v_fmac_f32_e32 v123, v134, v134
	v_add_f32_e32 v122, v122, v123
	v_mul_f32_e32 v123, v133, v133
	v_mul_f32_e32 v138, v131, v131
	v_fmac_f32_e32 v123, v132, v132
	v_fmac_f32_e32 v138, v130, v130
	v_add_f32_e32 v123, v123, v138
	v_add_f32_e32 v122, v122, v123
	v_mul_f32_e32 v123, v129, v129
	v_mul_f32_e32 v138, v127, v127
	v_fmac_f32_e32 v123, v128, v128
	v_fmac_f32_e32 v138, v126, v126
	v_add_f32_e32 v123, v123, v138
	v_add_f32_e32 v122, v123, v122
	v_mul_f32_e32 v123, v125, v125
	v_mul_f32_e32 v138, v121, v121
	v_fmac_f32_e32 v123, v124, v124
	v_fmac_f32_e32 v138, v120, v120
	v_add_f32_e32 v123, v123, v138
	v_add_f32_e32 v122, v123, v122
	ds_bpermute_b32 v123, v166, v122
	s_andn2_b64 vcc, exec, s[64:65]
	s_waitcnt lgkmcnt(0)
	v_add_f32_e32 v122, v122, v123
	ds_bpermute_b32 v123, v167, v122
	s_waitcnt lgkmcnt(0)
	v_add_f32_e32 v122, v122, v123
	ds_bpermute_b32 v123, v168, v122
	s_waitcnt lgkmcnt(0)
	v_add_f32_e32 v122, v122, v123
	ds_bpermute_b32 v123, v169, v122
	s_waitcnt lgkmcnt(0)
	v_add_f32_e32 v122, v122, v123
	ds_bpermute_b32 v123, v170, v122
	s_waitcnt lgkmcnt(0)
	v_add_f32_e32 v122, v122, v123
	ds_bpermute_b32 v123, v171, v122
	s_cbranch_vccnz .LBB0_3044
	s_waitcnt lgkmcnt(0)
	v_add_f32_e32 v122, v122, v123
	v_fmamk_f32 v122, v122, 0x3a800000, v165
	v_rsq_f32_e32 v122, v122
	s_lshl_b64 s[0:1], s[22:23], 12
	v_pk_mul_f32 v[138:139], v[136:137], v[122:123] op_sel_hi:[1,0]
	v_pk_mul_f32 v[134:135], v[134:135], v[122:123] op_sel_hi:[1,0]
	v_pk_mul_f32 v[130:131], v[130:131], v[122:123] op_sel_hi:[1,0]
	s_waitcnt vmcnt(2)
	v_pk_mul_f32 v[136:137], v[94:95], v[134:135]
	v_pk_mul_f32 v[134:135], v[92:93], v[138:139]
	v_lshl_add_u64 v[138:139], v[148:149], 0, s[0:1]
	global_store_dwordx4 v[138:139], v[134:137], off nt
	v_pk_mul_f32 v[126:127], v[126:127], v[122:123] op_sel_hi:[1,0]
	v_pk_mul_f32 v[124:125], v[124:125], v[122:123] op_sel_hi:[1,0]
	v_pk_mul_f32 v[134:135], v[132:133], v[122:123] op_sel_hi:[1,0]
	v_pk_mul_f32 v[132:133], v[90:91], v[130:131]
	v_pk_mul_f32 v[130:131], v[88:89], v[134:135]
	global_store_dwordx4 v[138:139], v[130:133], off offset:16 nt
	v_pk_mul_f32 v[120:121], v[120:121], v[122:123] op_sel_hi:[1,0]
	s_nop 0
	v_pk_mul_f32 v[130:131], v[128:129], v[122:123] op_sel_hi:[1,0]
	s_waitcnt vmcnt(2)
	v_pk_mul_f32 v[128:129], v[82:83], v[126:127]
	v_pk_mul_f32 v[126:127], v[80:81], v[130:131]
	v_pk_mul_f32 v[122:123], v[78:79], v[120:121]
	v_pk_mul_f32 v[120:121], v[76:77], v[124:125]
	global_store_dwordx4 v[138:139], v[126:129], off offset:2048 nt
	global_store_dwordx4 v[138:139], v[120:123], off offset:2064 nt
.LBB0_3044:
	s_nop 0
	v_and_b32_e32 v129, 0xffff0000, v116
	v_and_b32_e32 v127, 0xffff0000, v117
	v_lshlrev_b32_e32 v128, 16, v116
	v_lshlrev_b32_e32 v126, 16, v117
	v_lshlrev_b32_e32 v124, 16, v118
	v_and_b32_e32 v125, 0xffff0000, v118
	v_lshlrev_b32_e32 v122, 16, v119
	s_waitcnt lgkmcnt(0)
	v_and_b32_e32 v123, 0xffff0000, v119
	v_lshlrev_b32_e32 v120, 16, v112
	v_and_b32_e32 v121, 0xffff0000, v112
	v_lshlrev_b32_e32 v118, 16, v113
	v_and_b32_e32 v119, 0xffff0000, v113
	v_lshlrev_b32_e32 v116, 16, v114
	v_and_b32_e32 v117, 0xffff0000, v114
	v_lshlrev_b32_e32 v112, 16, v115
	v_and_b32_e32 v113, 0xffff0000, v115
	v_mul_f32_e32 v114, v129, v129
	v_mul_f32_e32 v115, v127, v127
	v_fmac_f32_e32 v114, v128, v128
	v_fmac_f32_e32 v115, v126, v126
	v_add_f32_e32 v114, v114, v115
	v_mul_f32_e32 v115, v125, v125
	v_mul_f32_e32 v130, v123, v123
	v_fmac_f32_e32 v115, v124, v124
	v_fmac_f32_e32 v130, v122, v122
	v_add_f32_e32 v115, v115, v130
	v_add_f32_e32 v114, v114, v115
	v_mul_f32_e32 v115, v121, v121
	v_mul_f32_e32 v130, v119, v119
	v_fmac_f32_e32 v115, v120, v120
	v_fmac_f32_e32 v130, v118, v118
	v_add_f32_e32 v115, v115, v130
	v_add_f32_e32 v114, v115, v114
	v_mul_f32_e32 v115, v117, v117
	v_mul_f32_e32 v130, v113, v113
	v_fmac_f32_e32 v115, v116, v116
	v_fmac_f32_e32 v130, v112, v112
	v_add_f32_e32 v115, v115, v130
	v_add_f32_e32 v114, v115, v114
	ds_bpermute_b32 v115, v166, v114
	s_andn2_b64 vcc, exec, s[62:63]
	s_waitcnt lgkmcnt(0)
	v_add_f32_e32 v114, v114, v115
	ds_bpermute_b32 v115, v167, v114
	s_waitcnt lgkmcnt(0)
	v_add_f32_e32 v114, v114, v115
	ds_bpermute_b32 v115, v168, v114
	s_waitcnt lgkmcnt(0)
	v_add_f32_e32 v114, v114, v115
	ds_bpermute_b32 v115, v169, v114
	s_waitcnt lgkmcnt(0)
	v_add_f32_e32 v114, v114, v115
	ds_bpermute_b32 v115, v170, v114
	s_waitcnt lgkmcnt(0)
	v_add_f32_e32 v114, v114, v115
	ds_bpermute_b32 v115, v171, v114
	s_cbranch_vccnz .LBB0_3046
	s_waitcnt lgkmcnt(0)
	v_add_f32_e32 v114, v114, v115
	v_fmamk_f32 v114, v114, 0x3a800000, v165
	v_rsq_f32_e32 v114, v114
	s_lshl_b64 s[0:1], s[20:21], 12
	v_pk_mul_f32 v[130:131], v[128:129], v[114:115] op_sel_hi:[1,0]
	v_pk_mul_f32 v[126:127], v[126:127], v[114:115] op_sel_hi:[1,0]
	v_pk_mul_f32 v[122:123], v[122:123], v[114:115] op_sel_hi:[1,0]
	s_waitcnt vmcnt(2)
	v_pk_mul_f32 v[128:129], v[94:95], v[126:127]
	v_pk_mul_f32 v[126:127], v[92:93], v[130:131]
	v_lshl_add_u64 v[130:131], v[148:149], 0, s[0:1]
	global_store_dwordx4 v[130:131], v[126:129], off nt
	v_pk_mul_f32 v[118:119], v[118:119], v[114:115] op_sel_hi:[1,0]
	v_pk_mul_f32 v[116:117], v[116:117], v[114:115] op_sel_hi:[1,0]
	v_pk_mul_f32 v[126:127], v[124:125], v[114:115] op_sel_hi:[1,0]
	v_pk_mul_f32 v[124:125], v[90:91], v[122:123]
	v_pk_mul_f32 v[122:123], v[88:89], v[126:127]
	global_store_dwordx4 v[130:131], v[122:125], off offset:16 nt
	v_pk_mul_f32 v[112:113], v[112:113], v[114:115] op_sel_hi:[1,0]
	s_nop 0
	v_pk_mul_f32 v[122:123], v[120:121], v[114:115] op_sel_hi:[1,0]
	s_waitcnt vmcnt(2)
	v_pk_mul_f32 v[120:121], v[82:83], v[118:119]
	v_pk_mul_f32 v[118:119], v[80:81], v[122:123]
	v_pk_mul_f32 v[114:115], v[78:79], v[112:113]
	v_pk_mul_f32 v[112:113], v[76:77], v[116:117]
	global_store_dwordx4 v[130:131], v[118:121], off offset:2048 nt
	global_store_dwordx4 v[130:131], v[112:115], off offset:2064 nt
.LBB0_3046:
	s_nop 0
	v_and_b32_e32 v121, 0xffff0000, v108
	v_and_b32_e32 v119, 0xffff0000, v109
	v_lshlrev_b32_e32 v120, 16, v108
	v_lshlrev_b32_e32 v118, 16, v109
	v_lshlrev_b32_e32 v116, 16, v110
	v_and_b32_e32 v117, 0xffff0000, v110
	v_lshlrev_b32_e32 v114, 16, v111
	s_waitcnt lgkmcnt(0)
	v_and_b32_e32 v115, 0xffff0000, v111
	v_lshlrev_b32_e32 v112, 16, v104
	v_and_b32_e32 v113, 0xffff0000, v104
	v_lshlrev_b32_e32 v110, 16, v105
	v_and_b32_e32 v111, 0xffff0000, v105
	v_lshlrev_b32_e32 v108, 16, v106
	v_and_b32_e32 v109, 0xffff0000, v106
	v_lshlrev_b32_e32 v104, 16, v107
	v_and_b32_e32 v105, 0xffff0000, v107
	v_mul_f32_e32 v106, v121, v121
	v_mul_f32_e32 v107, v119, v119
	v_fmac_f32_e32 v106, v120, v120
	v_fmac_f32_e32 v107, v118, v118
	v_add_f32_e32 v106, v106, v107
	v_mul_f32_e32 v107, v117, v117
	v_mul_f32_e32 v122, v115, v115
	v_fmac_f32_e32 v107, v116, v116
	v_fmac_f32_e32 v122, v114, v114
	v_add_f32_e32 v107, v107, v122
	v_add_f32_e32 v106, v106, v107
	v_mul_f32_e32 v107, v113, v113
	v_mul_f32_e32 v122, v111, v111
	v_fmac_f32_e32 v107, v112, v112
	v_fmac_f32_e32 v122, v110, v110
	v_add_f32_e32 v107, v107, v122
	v_add_f32_e32 v106, v107, v106
	v_mul_f32_e32 v107, v109, v109
	v_mul_f32_e32 v122, v105, v105
	v_fmac_f32_e32 v107, v108, v108
	v_fmac_f32_e32 v122, v104, v104
	v_add_f32_e32 v107, v107, v122
	v_add_f32_e32 v106, v107, v106
	ds_bpermute_b32 v107, v166, v106
	s_andn2_b64 vcc, exec, s[60:61]
	s_waitcnt lgkmcnt(0)
	v_add_f32_e32 v106, v106, v107
	ds_bpermute_b32 v107, v167, v106
	s_waitcnt lgkmcnt(0)
	v_add_f32_e32 v106, v106, v107
	ds_bpermute_b32 v107, v168, v106
	s_waitcnt lgkmcnt(0)
	v_add_f32_e32 v106, v106, v107
	ds_bpermute_b32 v107, v169, v106
	s_waitcnt lgkmcnt(0)
	v_add_f32_e32 v106, v106, v107
	ds_bpermute_b32 v107, v170, v106
	s_waitcnt lgkmcnt(0)
	v_add_f32_e32 v106, v106, v107
	ds_bpermute_b32 v107, v171, v106
	s_cbranch_vccnz .LBB0_3048
	s_waitcnt lgkmcnt(0)
	v_add_f32_e32 v106, v106, v107
	v_fmamk_f32 v106, v106, 0x3a800000, v165
	v_rsq_f32_e32 v106, v106
	s_lshl_b64 s[0:1], s[18:19], 12
	v_pk_mul_f32 v[122:123], v[120:121], v[106:107] op_sel_hi:[1,0]
	v_pk_mul_f32 v[118:119], v[118:119], v[106:107] op_sel_hi:[1,0]
	v_pk_mul_f32 v[114:115], v[114:115], v[106:107] op_sel_hi:[1,0]
	s_waitcnt vmcnt(2)
	v_pk_mul_f32 v[120:121], v[94:95], v[118:119]
	v_pk_mul_f32 v[118:119], v[92:93], v[122:123]
	v_lshl_add_u64 v[122:123], v[148:149], 0, s[0:1]
	global_store_dwordx4 v[122:123], v[118:121], off nt
	v_pk_mul_f32 v[110:111], v[110:111], v[106:107] op_sel_hi:[1,0]
	v_pk_mul_f32 v[108:109], v[108:109], v[106:107] op_sel_hi:[1,0]
	v_pk_mul_f32 v[118:119], v[116:117], v[106:107] op_sel_hi:[1,0]
	v_pk_mul_f32 v[116:117], v[90:91], v[114:115]
	v_pk_mul_f32 v[114:115], v[88:89], v[118:119]
	global_store_dwordx4 v[122:123], v[114:117], off offset:16 nt
	v_pk_mul_f32 v[104:105], v[104:105], v[106:107] op_sel_hi:[1,0]
	s_nop 0
	v_pk_mul_f32 v[114:115], v[112:113], v[106:107] op_sel_hi:[1,0]
	s_waitcnt vmcnt(2)
	v_pk_mul_f32 v[112:113], v[82:83], v[110:111]
	v_pk_mul_f32 v[110:111], v[80:81], v[114:115]
	v_pk_mul_f32 v[106:107], v[78:79], v[104:105]
	v_pk_mul_f32 v[104:105], v[76:77], v[108:109]
	global_store_dwordx4 v[122:123], v[110:113], off offset:2048 nt
	global_store_dwordx4 v[122:123], v[104:107], off offset:2064 nt
.LBB0_3048:
	s_nop 0
	v_and_b32_e32 v113, 0xffff0000, v100
	v_and_b32_e32 v111, 0xffff0000, v101
	v_lshlrev_b32_e32 v112, 16, v100
	v_lshlrev_b32_e32 v110, 16, v101
	v_lshlrev_b32_e32 v108, 16, v102
	v_and_b32_e32 v109, 0xffff0000, v102
	v_lshlrev_b32_e32 v106, 16, v103
	s_waitcnt lgkmcnt(0)
	v_and_b32_e32 v107, 0xffff0000, v103
	v_lshlrev_b32_e32 v104, 16, v96
	v_and_b32_e32 v105, 0xffff0000, v96
	v_lshlrev_b32_e32 v102, 16, v97
	v_and_b32_e32 v103, 0xffff0000, v97
	v_lshlrev_b32_e32 v100, 16, v98
	v_and_b32_e32 v101, 0xffff0000, v98
	v_lshlrev_b32_e32 v96, 16, v99
	v_and_b32_e32 v97, 0xffff0000, v99
	v_mul_f32_e32 v98, v113, v113
	v_mul_f32_e32 v99, v111, v111
	v_fmac_f32_e32 v98, v112, v112
	v_fmac_f32_e32 v99, v110, v110
	v_add_f32_e32 v98, v98, v99
	v_mul_f32_e32 v99, v109, v109
	v_mul_f32_e32 v114, v107, v107
	v_fmac_f32_e32 v99, v108, v108
	v_fmac_f32_e32 v114, v106, v106
	v_add_f32_e32 v99, v99, v114
	v_add_f32_e32 v98, v98, v99
	v_mul_f32_e32 v99, v105, v105
	v_mul_f32_e32 v114, v103, v103
	v_fmac_f32_e32 v99, v104, v104
	v_fmac_f32_e32 v114, v102, v102
	v_add_f32_e32 v99, v99, v114
	v_add_f32_e32 v98, v99, v98
	v_mul_f32_e32 v99, v101, v101
	v_mul_f32_e32 v114, v97, v97
	v_fmac_f32_e32 v99, v100, v100
	v_fmac_f32_e32 v114, v96, v96
	v_add_f32_e32 v99, v99, v114
	v_add_f32_e32 v98, v99, v98
	ds_bpermute_b32 v99, v166, v98
	s_andn2_b64 vcc, exec, s[58:59]
	s_waitcnt lgkmcnt(0)
	v_add_f32_e32 v98, v98, v99
	ds_bpermute_b32 v99, v167, v98
	s_waitcnt lgkmcnt(0)
	v_add_f32_e32 v98, v98, v99
	ds_bpermute_b32 v99, v168, v98
	s_waitcnt lgkmcnt(0)
	v_add_f32_e32 v98, v98, v99
	ds_bpermute_b32 v99, v169, v98
	s_waitcnt lgkmcnt(0)
	v_add_f32_e32 v98, v98, v99
	ds_bpermute_b32 v99, v170, v98
	s_waitcnt lgkmcnt(0)
	v_add_f32_e32 v98, v98, v99
	ds_bpermute_b32 v99, v171, v98
	s_cbranch_vccnz .LBB0_3050
	s_waitcnt lgkmcnt(0)
	v_add_f32_e32 v98, v98, v99
	v_fmamk_f32 v98, v98, 0x3a800000, v165
	v_rsq_f32_e32 v98, v98
	s_lshl_b64 s[0:1], s[16:17], 12
	v_pk_mul_f32 v[114:115], v[112:113], v[98:99] op_sel_hi:[1,0]
	v_pk_mul_f32 v[110:111], v[110:111], v[98:99] op_sel_hi:[1,0]
	v_pk_mul_f32 v[106:107], v[106:107], v[98:99] op_sel_hi:[1,0]
	s_waitcnt vmcnt(2)
	v_pk_mul_f32 v[112:113], v[94:95], v[110:111]
	v_pk_mul_f32 v[110:111], v[92:93], v[114:115]
	v_lshl_add_u64 v[114:115], v[148:149], 0, s[0:1]
	global_store_dwordx4 v[114:115], v[110:113], off nt
	v_pk_mul_f32 v[102:103], v[102:103], v[98:99] op_sel_hi:[1,0]
	v_pk_mul_f32 v[100:101], v[100:101], v[98:99] op_sel_hi:[1,0]
	v_pk_mul_f32 v[110:111], v[108:109], v[98:99] op_sel_hi:[1,0]
	v_pk_mul_f32 v[108:109], v[90:91], v[106:107]
	v_pk_mul_f32 v[106:107], v[88:89], v[110:111]
	global_store_dwordx4 v[114:115], v[106:109], off offset:16 nt
	v_pk_mul_f32 v[96:97], v[96:97], v[98:99] op_sel_hi:[1,0]
	s_nop 0
	v_pk_mul_f32 v[106:107], v[104:105], v[98:99] op_sel_hi:[1,0]
	s_waitcnt vmcnt(2)
	v_pk_mul_f32 v[104:105], v[82:83], v[102:103]
	v_pk_mul_f32 v[102:103], v[80:81], v[106:107]
	v_pk_mul_f32 v[98:99], v[78:79], v[96:97]
	v_pk_mul_f32 v[96:97], v[76:77], v[100:101]
	global_store_dwordx4 v[114:115], v[102:105], off offset:2048 nt
	global_store_dwordx4 v[114:115], v[96:99], off offset:2064 nt
.LBB0_3050:
	s_nop 0
	v_and_b32_e32 v105, 0xffff0000, v84
	v_and_b32_e32 v103, 0xffff0000, v85
	v_lshlrev_b32_e32 v104, 16, v84
	v_lshlrev_b32_e32 v102, 16, v85
	v_lshlrev_b32_e32 v100, 16, v86
	v_and_b32_e32 v101, 0xffff0000, v86
	v_lshlrev_b32_e32 v98, 16, v87
	s_waitcnt lgkmcnt(0)
	v_and_b32_e32 v99, 0xffff0000, v87
	v_lshlrev_b32_e32 v96, 16, v72
	v_and_b32_e32 v97, 0xffff0000, v72
	v_lshlrev_b32_e32 v86, 16, v73
	v_and_b32_e32 v87, 0xffff0000, v73
	v_lshlrev_b32_e32 v84, 16, v74
	v_and_b32_e32 v85, 0xffff0000, v74
	v_lshlrev_b32_e32 v72, 16, v75
	v_and_b32_e32 v73, 0xffff0000, v75
	v_mul_f32_e32 v74, v105, v105
	v_mul_f32_e32 v75, v103, v103
	v_fmac_f32_e32 v74, v104, v104
	v_fmac_f32_e32 v75, v102, v102
	v_add_f32_e32 v74, v74, v75
	v_mul_f32_e32 v75, v101, v101
	v_mul_f32_e32 v106, v99, v99
	v_fmac_f32_e32 v75, v100, v100
	v_fmac_f32_e32 v106, v98, v98
	v_add_f32_e32 v75, v75, v106
	v_add_f32_e32 v74, v74, v75
	v_mul_f32_e32 v75, v97, v97
	v_mul_f32_e32 v106, v87, v87
	v_fmac_f32_e32 v75, v96, v96
	v_fmac_f32_e32 v106, v86, v86
	v_add_f32_e32 v75, v75, v106
	v_add_f32_e32 v74, v75, v74
	v_mul_f32_e32 v75, v85, v85
	v_mul_f32_e32 v106, v73, v73
	v_fmac_f32_e32 v75, v84, v84
	v_fmac_f32_e32 v106, v72, v72
	v_add_f32_e32 v75, v75, v106
	v_add_f32_e32 v74, v75, v74
	ds_bpermute_b32 v75, v166, v74
	s_andn2_b64 vcc, exec, s[56:57]
	s_waitcnt lgkmcnt(0)
	v_add_f32_e32 v74, v74, v75
	ds_bpermute_b32 v75, v167, v74
	s_waitcnt lgkmcnt(0)
	v_add_f32_e32 v74, v74, v75
	ds_bpermute_b32 v75, v168, v74
	s_waitcnt lgkmcnt(0)
	v_add_f32_e32 v74, v74, v75
	ds_bpermute_b32 v75, v169, v74
	s_waitcnt lgkmcnt(0)
	v_add_f32_e32 v74, v74, v75
	ds_bpermute_b32 v75, v170, v74
	s_waitcnt lgkmcnt(0)
	v_add_f32_e32 v74, v74, v75
	ds_bpermute_b32 v75, v171, v74
	s_cbranch_vccnz .LBB0_3052
	s_waitcnt lgkmcnt(0)
	v_add_f32_e32 v74, v74, v75
	v_fmamk_f32 v74, v74, 0x3a800000, v165
	v_rsq_f32_e32 v74, v74
	s_lshl_b64 s[0:1], s[14:15], 12
	v_pk_mul_f32 v[106:107], v[104:105], v[74:75] op_sel_hi:[1,0]
	v_pk_mul_f32 v[102:103], v[102:103], v[74:75] op_sel_hi:[1,0]
	v_pk_mul_f32 v[98:99], v[98:99], v[74:75] op_sel_hi:[1,0]
	s_waitcnt vmcnt(2)
	v_pk_mul_f32 v[104:105], v[94:95], v[102:103]
	v_pk_mul_f32 v[102:103], v[92:93], v[106:107]
	v_lshl_add_u64 v[106:107], v[148:149], 0, s[0:1]
	global_store_dwordx4 v[106:107], v[102:105], off nt
	v_pk_mul_f32 v[96:97], v[96:97], v[74:75] op_sel_hi:[1,0]
	v_pk_mul_f32 v[86:87], v[86:87], v[74:75] op_sel_hi:[1,0]
	v_pk_mul_f32 v[102:103], v[100:101], v[74:75] op_sel_hi:[1,0]
	v_pk_mul_f32 v[100:101], v[90:91], v[98:99]
	v_pk_mul_f32 v[98:99], v[88:89], v[102:103]
	v_pk_mul_f32 v[84:85], v[84:85], v[74:75] op_sel_hi:[1,0]
	v_pk_mul_f32 v[72:73], v[72:73], v[74:75] op_sel_hi:[1,0]
	global_store_dwordx4 v[106:107], v[98:101], off offset:16 nt
	s_waitcnt vmcnt(2)
	v_pk_mul_f32 v[96:97], v[80:81], v[96:97]
	v_pk_mul_f32 v[74:75], v[78:79], v[72:73]
	v_pk_mul_f32 v[98:99], v[82:83], v[86:87]
	v_pk_mul_f32 v[72:73], v[76:77], v[84:85]
	global_store_dwordx4 v[106:107], v[96:99], off offset:2048 nt
	global_store_dwordx4 v[106:107], v[72:75], off offset:2064 nt
.LBB0_3052:
	s_nop 0
	v_and_b32_e32 v97, 0xffff0000, v68
	v_and_b32_e32 v87, 0xffff0000, v69
	v_lshlrev_b32_e32 v96, 16, v68
	v_lshlrev_b32_e32 v86, 16, v69
	v_lshlrev_b32_e32 v84, 16, v70
	v_and_b32_e32 v85, 0xffff0000, v70
	v_lshlrev_b32_e32 v74, 16, v71
	s_waitcnt lgkmcnt(0)
	v_and_b32_e32 v75, 0xffff0000, v71
	v_lshlrev_b32_e32 v72, 16, v64
	v_and_b32_e32 v73, 0xffff0000, v64
	v_lshlrev_b32_e32 v70, 16, v65
	v_and_b32_e32 v71, 0xffff0000, v65
	v_lshlrev_b32_e32 v68, 16, v66
	v_and_b32_e32 v69, 0xffff0000, v66
	v_lshlrev_b32_e32 v64, 16, v67
	v_and_b32_e32 v65, 0xffff0000, v67
	v_mul_f32_e32 v66, v97, v97
	v_mul_f32_e32 v67, v87, v87
	v_fmac_f32_e32 v66, v96, v96
	v_fmac_f32_e32 v67, v86, v86
	v_add_f32_e32 v66, v66, v67
	v_mul_f32_e32 v67, v85, v85
	v_mul_f32_e32 v98, v75, v75
	v_fmac_f32_e32 v67, v84, v84
	v_fmac_f32_e32 v98, v74, v74
	v_add_f32_e32 v67, v67, v98
	v_add_f32_e32 v66, v66, v67
	v_mul_f32_e32 v67, v73, v73
	v_mul_f32_e32 v98, v71, v71
	v_fmac_f32_e32 v67, v72, v72
	v_fmac_f32_e32 v98, v70, v70
	v_add_f32_e32 v67, v67, v98
	v_add_f32_e32 v66, v67, v66
	v_mul_f32_e32 v67, v69, v69
	v_mul_f32_e32 v98, v65, v65
	v_fmac_f32_e32 v67, v68, v68
	v_fmac_f32_e32 v98, v64, v64
	v_add_f32_e32 v67, v67, v98
	v_add_f32_e32 v66, v67, v66
	ds_bpermute_b32 v67, v166, v66
	s_andn2_b64 vcc, exec, s[54:55]
	s_waitcnt lgkmcnt(0)
	v_add_f32_e32 v66, v66, v67
	ds_bpermute_b32 v67, v167, v66
	s_waitcnt lgkmcnt(0)
	v_add_f32_e32 v66, v66, v67
	ds_bpermute_b32 v67, v168, v66
	s_waitcnt lgkmcnt(0)
	v_add_f32_e32 v66, v66, v67
	ds_bpermute_b32 v67, v169, v66
	s_waitcnt lgkmcnt(0)
	v_add_f32_e32 v66, v66, v67
	ds_bpermute_b32 v67, v170, v66
	s_waitcnt lgkmcnt(0)
	v_add_f32_e32 v66, v66, v67
	ds_bpermute_b32 v67, v171, v66
	s_cbranch_vccnz .LBB0_3054
	s_waitcnt lgkmcnt(0)
	v_add_f32_e32 v66, v66, v67
	v_fmamk_f32 v66, v66, 0x3a800000, v165
	v_rsq_f32_e32 v66, v66
	s_lshl_b64 s[0:1], s[12:13], 12
	v_lshl_add_u64 v[100:101], v[148:149], 0, s[0:1]
	v_pk_mul_f32 v[86:87], v[86:87], v[66:67] op_sel_hi:[1,0]
	v_pk_mul_f32 v[74:75], v[74:75], v[66:67] op_sel_hi:[1,0]
	v_pk_mul_f32 v[96:97], v[96:97], v[66:67] op_sel_hi:[1,0]
	s_waitcnt vmcnt(2)
	v_pk_mul_f32 v[98:99], v[94:95], v[86:87]
	v_pk_mul_f32 v[84:85], v[84:85], v[66:67] op_sel_hi:[1,0]
	v_pk_mul_f32 v[86:87], v[90:91], v[74:75]
	v_pk_mul_f32 v[74:75], v[72:73], v[66:67] op_sel_hi:[1,0]
	v_pk_mul_f32 v[70:71], v[70:71], v[66:67] op_sel_hi:[1,0]
	v_pk_mul_f32 v[68:69], v[68:69], v[66:67] op_sel_hi:[1,0]
	v_pk_mul_f32 v[64:65], v[64:65], v[66:67] op_sel_hi:[1,0]
	v_pk_mul_f32 v[96:97], v[92:93], v[96:97]
	v_pk_mul_f32 v[84:85], v[88:89], v[84:85]
	s_waitcnt vmcnt(0)
	v_pk_mul_f32 v[72:73], v[82:83], v[70:71]
	v_pk_mul_f32 v[70:71], v[80:81], v[74:75]
	v_pk_mul_f32 v[66:67], v[78:79], v[64:65]
	v_pk_mul_f32 v[64:65], v[76:77], v[68:69]
	global_store_dwordx4 v[100:101], v[96:99], off nt
	global_store_dwordx4 v[100:101], v[84:87], off offset:16 nt
	global_store_dwordx4 v[100:101], v[70:73], off offset:2048 nt
	global_store_dwordx4 v[100:101], v[64:67], off offset:2064 nt
.LBB0_3054:
	s_nop 0
	v_and_b32_e32 v73, 0xffff0000, v60
	v_and_b32_e32 v71, 0xffff0000, v61
	v_lshlrev_b32_e32 v72, 16, v60
	v_lshlrev_b32_e32 v70, 16, v61
	v_lshlrev_b32_e32 v68, 16, v62
	v_and_b32_e32 v69, 0xffff0000, v62
	v_lshlrev_b32_e32 v66, 16, v63
	s_waitcnt lgkmcnt(0)
	v_and_b32_e32 v67, 0xffff0000, v63
	v_lshlrev_b32_e32 v64, 16, v56
	v_and_b32_e32 v65, 0xffff0000, v56
	v_lshlrev_b32_e32 v62, 16, v57
	v_and_b32_e32 v63, 0xffff0000, v57
	v_lshlrev_b32_e32 v60, 16, v58
	v_and_b32_e32 v61, 0xffff0000, v58
	v_lshlrev_b32_e32 v56, 16, v59
	v_and_b32_e32 v57, 0xffff0000, v59
	v_mul_f32_e32 v58, v73, v73
	v_mul_f32_e32 v59, v71, v71
	v_fmac_f32_e32 v58, v72, v72
	v_fmac_f32_e32 v59, v70, v70
	v_add_f32_e32 v58, v58, v59
	v_mul_f32_e32 v59, v69, v69
	v_mul_f32_e32 v74, v67, v67
	v_fmac_f32_e32 v59, v68, v68
	v_fmac_f32_e32 v74, v66, v66
	v_add_f32_e32 v59, v59, v74
	v_add_f32_e32 v58, v58, v59
	v_mul_f32_e32 v59, v65, v65
	v_mul_f32_e32 v74, v63, v63
	v_fmac_f32_e32 v59, v64, v64
	v_fmac_f32_e32 v74, v62, v62
	v_add_f32_e32 v59, v59, v74
	v_add_f32_e32 v58, v59, v58
	v_mul_f32_e32 v59, v61, v61
	v_mul_f32_e32 v74, v57, v57
	v_fmac_f32_e32 v59, v60, v60
	v_fmac_f32_e32 v74, v56, v56
	v_add_f32_e32 v59, v59, v74
	v_add_f32_e32 v58, v59, v58
	ds_bpermute_b32 v59, v166, v58
	s_andn2_b64 vcc, exec, s[52:53]
	s_waitcnt lgkmcnt(0)
	v_add_f32_e32 v58, v58, v59
	ds_bpermute_b32 v59, v167, v58
	s_waitcnt lgkmcnt(0)
	v_add_f32_e32 v58, v58, v59
	ds_bpermute_b32 v59, v168, v58
	s_waitcnt lgkmcnt(0)
	v_add_f32_e32 v58, v58, v59
	ds_bpermute_b32 v59, v169, v58
	s_waitcnt lgkmcnt(0)
	v_add_f32_e32 v58, v58, v59
	ds_bpermute_b32 v59, v170, v58
	s_waitcnt lgkmcnt(0)
	v_add_f32_e32 v58, v58, v59
	ds_bpermute_b32 v59, v171, v58
	s_cbranch_vccnz .LBB0_3056
	s_waitcnt lgkmcnt(0)
	v_add_f32_e32 v58, v58, v59
	v_fmamk_f32 v58, v58, 0x3a800000, v165
	v_rsq_f32_e32 v58, v58
	s_lshl_b64 s[0:1], s[10:11], 12
	v_pk_mul_f32 v[74:75], v[72:73], v[58:59] op_sel_hi:[1,0]
	v_pk_mul_f32 v[70:71], v[70:71], v[58:59] op_sel_hi:[1,0]
	v_pk_mul_f32 v[66:67], v[66:67], v[58:59] op_sel_hi:[1,0]
	s_waitcnt vmcnt(2)
	v_pk_mul_f32 v[72:73], v[94:95], v[70:71]
	v_pk_mul_f32 v[70:71], v[92:93], v[74:75]
	v_lshl_add_u64 v[74:75], v[148:149], 0, s[0:1]
	global_store_dwordx4 v[74:75], v[70:73], off nt
	v_pk_mul_f32 v[62:63], v[62:63], v[58:59] op_sel_hi:[1,0]
	v_pk_mul_f32 v[60:61], v[60:61], v[58:59] op_sel_hi:[1,0]
	v_pk_mul_f32 v[70:71], v[68:69], v[58:59] op_sel_hi:[1,0]
	v_pk_mul_f32 v[68:69], v[90:91], v[66:67]
	v_pk_mul_f32 v[66:67], v[88:89], v[70:71]
	global_store_dwordx4 v[74:75], v[66:69], off offset:16 nt
	v_pk_mul_f32 v[56:57], v[56:57], v[58:59] op_sel_hi:[1,0]
	s_nop 0
	v_pk_mul_f32 v[66:67], v[64:65], v[58:59] op_sel_hi:[1,0]
	s_waitcnt vmcnt(2)
	v_pk_mul_f32 v[64:65], v[82:83], v[62:63]
	v_pk_mul_f32 v[62:63], v[80:81], v[66:67]
	v_pk_mul_f32 v[58:59], v[78:79], v[56:57]
	v_pk_mul_f32 v[56:57], v[76:77], v[60:61]
	global_store_dwordx4 v[74:75], v[62:65], off offset:2048 nt
	global_store_dwordx4 v[74:75], v[56:59], off offset:2064 nt
.LBB0_3056:
	s_nop 0
	v_and_b32_e32 v65, 0xffff0000, v52
	v_and_b32_e32 v63, 0xffff0000, v53
	v_lshlrev_b32_e32 v64, 16, v52
	v_lshlrev_b32_e32 v62, 16, v53
	v_lshlrev_b32_e32 v60, 16, v54
	v_and_b32_e32 v61, 0xffff0000, v54
	v_lshlrev_b32_e32 v58, 16, v55
	s_waitcnt lgkmcnt(0)
	v_and_b32_e32 v59, 0xffff0000, v55
	v_lshlrev_b32_e32 v56, 16, v48
	v_and_b32_e32 v57, 0xffff0000, v48
	v_lshlrev_b32_e32 v54, 16, v49
	v_and_b32_e32 v55, 0xffff0000, v49
	v_lshlrev_b32_e32 v52, 16, v50
	v_and_b32_e32 v53, 0xffff0000, v50
	v_lshlrev_b32_e32 v48, 16, v51
	v_and_b32_e32 v49, 0xffff0000, v51
	v_mul_f32_e32 v50, v65, v65
	v_mul_f32_e32 v51, v63, v63
	v_fmac_f32_e32 v50, v64, v64
	v_fmac_f32_e32 v51, v62, v62
	v_add_f32_e32 v50, v50, v51
	v_mul_f32_e32 v51, v61, v61
	v_mul_f32_e32 v66, v59, v59
	v_fmac_f32_e32 v51, v60, v60
	v_fmac_f32_e32 v66, v58, v58
	v_add_f32_e32 v51, v51, v66
	v_add_f32_e32 v50, v50, v51
	v_mul_f32_e32 v51, v57, v57
	v_mul_f32_e32 v66, v55, v55
	v_fmac_f32_e32 v51, v56, v56
	v_fmac_f32_e32 v66, v54, v54
	v_add_f32_e32 v51, v51, v66
	v_add_f32_e32 v50, v51, v50
	v_mul_f32_e32 v51, v53, v53
	v_mul_f32_e32 v66, v49, v49
	v_fmac_f32_e32 v51, v52, v52
	v_fmac_f32_e32 v66, v48, v48
	v_add_f32_e32 v51, v51, v66
	v_add_f32_e32 v50, v51, v50
	ds_bpermute_b32 v51, v166, v50
	s_andn2_b64 vcc, exec, s[50:51]
	s_waitcnt lgkmcnt(0)
	v_add_f32_e32 v50, v50, v51
	ds_bpermute_b32 v51, v167, v50
	s_waitcnt lgkmcnt(0)
	v_add_f32_e32 v50, v50, v51
	ds_bpermute_b32 v51, v168, v50
	s_waitcnt lgkmcnt(0)
	v_add_f32_e32 v50, v50, v51
	ds_bpermute_b32 v51, v169, v50
	s_waitcnt lgkmcnt(0)
	v_add_f32_e32 v50, v50, v51
	ds_bpermute_b32 v51, v170, v50
	s_waitcnt lgkmcnt(0)
	v_add_f32_e32 v50, v50, v51
	ds_bpermute_b32 v51, v171, v50
	s_cbranch_vccnz .LBB0_3058
	s_waitcnt lgkmcnt(0)
	v_add_f32_e32 v50, v50, v51
	v_fmamk_f32 v50, v50, 0x3a800000, v165
	v_rsq_f32_e32 v50, v50
	s_lshl_b64 s[0:1], s[8:9], 12
	v_pk_mul_f32 v[66:67], v[64:65], v[50:51] op_sel_hi:[1,0]
	v_pk_mul_f32 v[62:63], v[62:63], v[50:51] op_sel_hi:[1,0]
	v_pk_mul_f32 v[58:59], v[58:59], v[50:51] op_sel_hi:[1,0]
	s_waitcnt vmcnt(2)
	v_pk_mul_f32 v[64:65], v[94:95], v[62:63]
	v_pk_mul_f32 v[62:63], v[92:93], v[66:67]
	v_lshl_add_u64 v[66:67], v[148:149], 0, s[0:1]
	global_store_dwordx4 v[66:67], v[62:65], off nt
	v_pk_mul_f32 v[54:55], v[54:55], v[50:51] op_sel_hi:[1,0]
	v_pk_mul_f32 v[52:53], v[52:53], v[50:51] op_sel_hi:[1,0]
	v_pk_mul_f32 v[62:63], v[60:61], v[50:51] op_sel_hi:[1,0]
	v_pk_mul_f32 v[60:61], v[90:91], v[58:59]
	v_pk_mul_f32 v[58:59], v[88:89], v[62:63]
	global_store_dwordx4 v[66:67], v[58:61], off offset:16 nt
	v_pk_mul_f32 v[48:49], v[48:49], v[50:51] op_sel_hi:[1,0]
	s_nop 0
	v_pk_mul_f32 v[58:59], v[56:57], v[50:51] op_sel_hi:[1,0]
	s_waitcnt vmcnt(2)
	v_pk_mul_f32 v[56:57], v[82:83], v[54:55]
	v_pk_mul_f32 v[54:55], v[80:81], v[58:59]
	v_pk_mul_f32 v[50:51], v[78:79], v[48:49]
	v_pk_mul_f32 v[48:49], v[76:77], v[52:53]
	global_store_dwordx4 v[66:67], v[54:57], off offset:2048 nt
	global_store_dwordx4 v[66:67], v[48:51], off offset:2064 nt
.LBB0_3058:
	s_nop 0
	v_and_b32_e32 v57, 0xffff0000, v44
	v_and_b32_e32 v55, 0xffff0000, v45
	v_lshlrev_b32_e32 v56, 16, v44
	v_lshlrev_b32_e32 v54, 16, v45
	v_lshlrev_b32_e32 v52, 16, v46
	v_and_b32_e32 v53, 0xffff0000, v46
	v_lshlrev_b32_e32 v50, 16, v47
	s_waitcnt lgkmcnt(0)
	v_and_b32_e32 v51, 0xffff0000, v47
	v_lshlrev_b32_e32 v48, 16, v40
	v_and_b32_e32 v49, 0xffff0000, v40
	v_lshlrev_b32_e32 v46, 16, v41
	v_and_b32_e32 v47, 0xffff0000, v41
	v_lshlrev_b32_e32 v44, 16, v42
	v_and_b32_e32 v45, 0xffff0000, v42
	v_lshlrev_b32_e32 v40, 16, v43
	v_and_b32_e32 v41, 0xffff0000, v43
	v_mul_f32_e32 v42, v57, v57
	v_mul_f32_e32 v43, v55, v55
	v_fmac_f32_e32 v42, v56, v56
	v_fmac_f32_e32 v43, v54, v54
	v_add_f32_e32 v42, v42, v43
	v_mul_f32_e32 v43, v53, v53
	v_mul_f32_e32 v58, v51, v51
	v_fmac_f32_e32 v43, v52, v52
	v_fmac_f32_e32 v58, v50, v50
	v_add_f32_e32 v43, v43, v58
	v_add_f32_e32 v42, v42, v43
	v_mul_f32_e32 v43, v49, v49
	v_mul_f32_e32 v58, v47, v47
	v_fmac_f32_e32 v43, v48, v48
	v_fmac_f32_e32 v58, v46, v46
	v_add_f32_e32 v43, v43, v58
	v_add_f32_e32 v42, v43, v42
	v_mul_f32_e32 v43, v45, v45
	v_mul_f32_e32 v58, v41, v41
	v_fmac_f32_e32 v43, v44, v44
	v_fmac_f32_e32 v58, v40, v40
	v_add_f32_e32 v43, v43, v58
	v_add_f32_e32 v42, v43, v42
	ds_bpermute_b32 v43, v166, v42
	s_andn2_b64 vcc, exec, s[48:49]
	s_waitcnt lgkmcnt(0)
	v_add_f32_e32 v42, v42, v43
	ds_bpermute_b32 v43, v167, v42
	s_waitcnt lgkmcnt(0)
	v_add_f32_e32 v42, v42, v43
	ds_bpermute_b32 v43, v168, v42
	s_waitcnt lgkmcnt(0)
	v_add_f32_e32 v42, v42, v43
	ds_bpermute_b32 v43, v169, v42
	s_waitcnt lgkmcnt(0)
	v_add_f32_e32 v42, v42, v43
	ds_bpermute_b32 v43, v170, v42
	s_waitcnt lgkmcnt(0)
	v_add_f32_e32 v42, v42, v43
	ds_bpermute_b32 v43, v171, v42
	s_cbranch_vccnz .LBB0_3060
	s_waitcnt lgkmcnt(0)
	v_add_f32_e32 v42, v42, v43
	v_fmamk_f32 v42, v42, 0x3a800000, v165
	v_rsq_f32_e32 v42, v42
	s_lshl_b64 s[0:1], s[6:7], 12
	v_pk_mul_f32 v[58:59], v[56:57], v[42:43] op_sel_hi:[1,0]
	v_pk_mul_f32 v[54:55], v[54:55], v[42:43] op_sel_hi:[1,0]
	v_pk_mul_f32 v[50:51], v[50:51], v[42:43] op_sel_hi:[1,0]
	s_waitcnt vmcnt(2)
	v_pk_mul_f32 v[56:57], v[94:95], v[54:55]
	v_pk_mul_f32 v[54:55], v[92:93], v[58:59]
	v_lshl_add_u64 v[58:59], v[148:149], 0, s[0:1]
	global_store_dwordx4 v[58:59], v[54:57], off nt
	v_pk_mul_f32 v[46:47], v[46:47], v[42:43] op_sel_hi:[1,0]
	v_pk_mul_f32 v[44:45], v[44:45], v[42:43] op_sel_hi:[1,0]
	v_pk_mul_f32 v[54:55], v[52:53], v[42:43] op_sel_hi:[1,0]
	v_pk_mul_f32 v[52:53], v[90:91], v[50:51]
	v_pk_mul_f32 v[50:51], v[88:89], v[54:55]
	global_store_dwordx4 v[58:59], v[50:53], off offset:16 nt
	v_pk_mul_f32 v[40:41], v[40:41], v[42:43] op_sel_hi:[1,0]
	s_nop 0
	v_pk_mul_f32 v[50:51], v[48:49], v[42:43] op_sel_hi:[1,0]
	s_waitcnt vmcnt(2)
	v_pk_mul_f32 v[48:49], v[82:83], v[46:47]
	v_pk_mul_f32 v[46:47], v[80:81], v[50:51]
	v_pk_mul_f32 v[42:43], v[78:79], v[40:41]
	v_pk_mul_f32 v[40:41], v[76:77], v[44:45]
	global_store_dwordx4 v[58:59], v[46:49], off offset:2048 nt
	global_store_dwordx4 v[58:59], v[40:43], off offset:2064 nt
.LBB0_3060:
	s_nop 0
	v_and_b32_e32 v49, 0xffff0000, v36
	v_and_b32_e32 v47, 0xffff0000, v37
	v_lshlrev_b32_e32 v48, 16, v36
	v_lshlrev_b32_e32 v46, 16, v37
	v_lshlrev_b32_e32 v44, 16, v38
	v_and_b32_e32 v45, 0xffff0000, v38
	v_lshlrev_b32_e32 v42, 16, v39
	s_waitcnt lgkmcnt(0)
	v_and_b32_e32 v43, 0xffff0000, v39
	v_lshlrev_b32_e32 v40, 16, v32
	v_and_b32_e32 v41, 0xffff0000, v32
	v_lshlrev_b32_e32 v38, 16, v33
	v_and_b32_e32 v39, 0xffff0000, v33
	v_lshlrev_b32_e32 v36, 16, v34
	v_and_b32_e32 v37, 0xffff0000, v34
	v_lshlrev_b32_e32 v32, 16, v35
	v_and_b32_e32 v33, 0xffff0000, v35
	v_mul_f32_e32 v34, v49, v49
	v_mul_f32_e32 v35, v47, v47
	v_fmac_f32_e32 v34, v48, v48
	v_fmac_f32_e32 v35, v46, v46
	v_add_f32_e32 v34, v34, v35
	v_mul_f32_e32 v35, v45, v45
	v_mul_f32_e32 v50, v43, v43
	v_fmac_f32_e32 v35, v44, v44
	v_fmac_f32_e32 v50, v42, v42
	v_add_f32_e32 v35, v35, v50
	v_add_f32_e32 v34, v34, v35
	v_mul_f32_e32 v35, v41, v41
	v_mul_f32_e32 v50, v39, v39
	v_fmac_f32_e32 v35, v40, v40
	v_fmac_f32_e32 v50, v38, v38
	v_add_f32_e32 v35, v35, v50
	v_add_f32_e32 v34, v35, v34
	v_mul_f32_e32 v35, v37, v37
	v_mul_f32_e32 v50, v33, v33
	v_fmac_f32_e32 v35, v36, v36
	v_fmac_f32_e32 v50, v32, v32
	v_add_f32_e32 v35, v35, v50
	v_add_f32_e32 v34, v35, v34
	ds_bpermute_b32 v35, v166, v34
	s_andn2_b64 vcc, exec, s[46:47]
	s_waitcnt lgkmcnt(0)
	v_add_f32_e32 v34, v34, v35
	ds_bpermute_b32 v35, v167, v34
	s_waitcnt lgkmcnt(0)
	v_add_f32_e32 v34, v34, v35
	ds_bpermute_b32 v35, v168, v34
	s_waitcnt lgkmcnt(0)
	v_add_f32_e32 v34, v34, v35
	ds_bpermute_b32 v35, v169, v34
	s_waitcnt lgkmcnt(0)
	v_add_f32_e32 v34, v34, v35
	ds_bpermute_b32 v35, v170, v34
	s_waitcnt lgkmcnt(0)
	v_add_f32_e32 v34, v34, v35
	ds_bpermute_b32 v35, v171, v34
	s_cbranch_vccnz .LBB0_3062
	s_waitcnt lgkmcnt(0)
	v_add_f32_e32 v34, v34, v35
	v_fmamk_f32 v34, v34, 0x3a800000, v165
	v_rsq_f32_e32 v34, v34
	s_lshl_b64 s[0:1], s[2:3], 12
	v_pk_mul_f32 v[50:51], v[48:49], v[34:35] op_sel_hi:[1,0]
	v_pk_mul_f32 v[46:47], v[46:47], v[34:35] op_sel_hi:[1,0]
	v_pk_mul_f32 v[42:43], v[42:43], v[34:35] op_sel_hi:[1,0]
	s_waitcnt vmcnt(2)
	v_pk_mul_f32 v[48:49], v[94:95], v[46:47]
	v_pk_mul_f32 v[46:47], v[92:93], v[50:51]
	v_lshl_add_u64 v[50:51], v[148:149], 0, s[0:1]
	global_store_dwordx4 v[50:51], v[46:49], off nt
	v_pk_mul_f32 v[38:39], v[38:39], v[34:35] op_sel_hi:[1,0]
	v_pk_mul_f32 v[36:37], v[36:37], v[34:35] op_sel_hi:[1,0]
	v_pk_mul_f32 v[46:47], v[44:45], v[34:35] op_sel_hi:[1,0]
	v_pk_mul_f32 v[44:45], v[90:91], v[42:43]
	v_pk_mul_f32 v[42:43], v[88:89], v[46:47]
	global_store_dwordx4 v[50:51], v[42:45], off offset:16 nt
	v_pk_mul_f32 v[32:33], v[32:33], v[34:35] op_sel_hi:[1,0]
	s_nop 0
	v_pk_mul_f32 v[42:43], v[40:41], v[34:35] op_sel_hi:[1,0]
	s_waitcnt vmcnt(2)
	v_pk_mul_f32 v[40:41], v[82:83], v[38:39]
	v_pk_mul_f32 v[38:39], v[80:81], v[42:43]
	v_pk_mul_f32 v[34:35], v[78:79], v[32:33]
	v_pk_mul_f32 v[32:33], v[76:77], v[36:37]
	global_store_dwordx4 v[50:51], v[38:41], off offset:2048 nt
	global_store_dwordx4 v[50:51], v[32:35], off offset:2064 nt
.LBB0_3062:
	s_nop 0
	v_and_b32_e32 v41, 0xffff0000, v28
	v_and_b32_e32 v39, 0xffff0000, v29
	v_lshlrev_b32_e32 v40, 16, v28
	v_lshlrev_b32_e32 v38, 16, v29
	v_lshlrev_b32_e32 v36, 16, v30
	v_and_b32_e32 v37, 0xffff0000, v30
	v_lshlrev_b32_e32 v34, 16, v31
	s_waitcnt lgkmcnt(0)
	v_and_b32_e32 v35, 0xffff0000, v31
	v_lshlrev_b32_e32 v32, 16, v24
	v_and_b32_e32 v33, 0xffff0000, v24
	v_lshlrev_b32_e32 v30, 16, v25
	v_and_b32_e32 v31, 0xffff0000, v25
	v_lshlrev_b32_e32 v28, 16, v26
	v_and_b32_e32 v29, 0xffff0000, v26
	v_lshlrev_b32_e32 v24, 16, v27
	v_and_b32_e32 v25, 0xffff0000, v27
	v_mul_f32_e32 v26, v41, v41
	v_mul_f32_e32 v27, v39, v39
	v_fmac_f32_e32 v26, v40, v40
	v_fmac_f32_e32 v27, v38, v38
	v_add_f32_e32 v26, v26, v27
	v_mul_f32_e32 v27, v37, v37
	v_mul_f32_e32 v42, v35, v35
	v_fmac_f32_e32 v27, v36, v36
	v_fmac_f32_e32 v42, v34, v34
	v_add_f32_e32 v27, v27, v42
	v_add_f32_e32 v26, v26, v27
	v_mul_f32_e32 v27, v33, v33
	v_mul_f32_e32 v42, v31, v31
	v_fmac_f32_e32 v27, v32, v32
	v_fmac_f32_e32 v42, v30, v30
	v_add_f32_e32 v27, v27, v42
	v_add_f32_e32 v26, v27, v26
	v_mul_f32_e32 v27, v29, v29
	v_mul_f32_e32 v42, v25, v25
	v_fmac_f32_e32 v27, v28, v28
	v_fmac_f32_e32 v42, v24, v24
	v_add_f32_e32 v27, v27, v42
	v_add_f32_e32 v26, v27, v26
	ds_bpermute_b32 v27, v166, v26
	s_andn2_b64 vcc, exec, s[44:45]
	s_waitcnt lgkmcnt(0)
	v_add_f32_e32 v26, v26, v27
	ds_bpermute_b32 v27, v167, v26
	s_waitcnt lgkmcnt(0)
	v_add_f32_e32 v26, v26, v27
	ds_bpermute_b32 v27, v168, v26
	s_waitcnt lgkmcnt(0)
	v_add_f32_e32 v26, v26, v27
	ds_bpermute_b32 v27, v169, v26
	s_waitcnt lgkmcnt(0)
	v_add_f32_e32 v26, v26, v27
	ds_bpermute_b32 v27, v170, v26
	s_waitcnt lgkmcnt(0)
	v_add_f32_e32 v26, v26, v27
	ds_bpermute_b32 v27, v171, v26
	s_cbranch_vccnz .LBB0_3064
	s_waitcnt lgkmcnt(0)
	v_add_f32_e32 v26, v26, v27
	v_fmamk_f32 v26, v26, 0x3a800000, v165
	v_rsq_f32_e32 v26, v26
	s_lshl_b64 s[0:1], s[4:5], 12
	v_pk_mul_f32 v[42:43], v[40:41], v[26:27] op_sel_hi:[1,0]
	v_pk_mul_f32 v[38:39], v[38:39], v[26:27] op_sel_hi:[1,0]
	v_pk_mul_f32 v[34:35], v[34:35], v[26:27] op_sel_hi:[1,0]
	s_waitcnt vmcnt(2)
	v_pk_mul_f32 v[40:41], v[94:95], v[38:39]
	v_pk_mul_f32 v[38:39], v[92:93], v[42:43]
	v_lshl_add_u64 v[42:43], v[148:149], 0, s[0:1]
	global_store_dwordx4 v[42:43], v[38:41], off nt
	v_pk_mul_f32 v[30:31], v[30:31], v[26:27] op_sel_hi:[1,0]
	v_pk_mul_f32 v[28:29], v[28:29], v[26:27] op_sel_hi:[1,0]
	v_pk_mul_f32 v[38:39], v[36:37], v[26:27] op_sel_hi:[1,0]
	v_pk_mul_f32 v[36:37], v[90:91], v[34:35]
	v_pk_mul_f32 v[34:35], v[88:89], v[38:39]
	global_store_dwordx4 v[42:43], v[34:37], off offset:16 nt
	v_pk_mul_f32 v[24:25], v[24:25], v[26:27] op_sel_hi:[1,0]
	s_nop 0
	v_pk_mul_f32 v[34:35], v[32:33], v[26:27] op_sel_hi:[1,0]
	s_waitcnt vmcnt(2)
	v_pk_mul_f32 v[32:33], v[82:83], v[30:31]
	v_pk_mul_f32 v[30:31], v[80:81], v[34:35]
	v_pk_mul_f32 v[26:27], v[78:79], v[24:25]
	v_pk_mul_f32 v[24:25], v[76:77], v[28:29]
	global_store_dwordx4 v[42:43], v[30:33], off offset:2048 nt
	global_store_dwordx4 v[42:43], v[24:27], off offset:2064 nt
.LBB0_3064:
	s_nop 0
	v_and_b32_e32 v33, 0xffff0000, v20
	v_and_b32_e32 v31, 0xffff0000, v21
	v_lshlrev_b32_e32 v32, 16, v20
	v_lshlrev_b32_e32 v30, 16, v21
	v_lshlrev_b32_e32 v28, 16, v22
	v_and_b32_e32 v29, 0xffff0000, v22
	v_lshlrev_b32_e32 v26, 16, v23
	s_waitcnt lgkmcnt(0)
	v_and_b32_e32 v27, 0xffff0000, v23
	v_lshlrev_b32_e32 v24, 16, v16
	v_and_b32_e32 v25, 0xffff0000, v16
	v_lshlrev_b32_e32 v22, 16, v17
	v_and_b32_e32 v23, 0xffff0000, v17
	v_lshlrev_b32_e32 v20, 16, v18
	v_and_b32_e32 v21, 0xffff0000, v18
	v_lshlrev_b32_e32 v16, 16, v19
	v_and_b32_e32 v17, 0xffff0000, v19
	v_mul_f32_e32 v18, v33, v33
	v_mul_f32_e32 v19, v31, v31
	v_fmac_f32_e32 v18, v32, v32
	v_fmac_f32_e32 v19, v30, v30
	v_add_f32_e32 v18, v18, v19
	v_mul_f32_e32 v19, v29, v29
	v_mul_f32_e32 v34, v27, v27
	v_fmac_f32_e32 v19, v28, v28
	v_fmac_f32_e32 v34, v26, v26
	v_add_f32_e32 v19, v19, v34
	v_add_f32_e32 v18, v18, v19
	v_mul_f32_e32 v19, v25, v25
	v_mul_f32_e32 v34, v23, v23
	v_fmac_f32_e32 v19, v24, v24
	v_fmac_f32_e32 v34, v22, v22
	v_add_f32_e32 v19, v19, v34
	v_add_f32_e32 v18, v19, v18
	v_mul_f32_e32 v19, v21, v21
	v_mul_f32_e32 v34, v17, v17
	v_fmac_f32_e32 v19, v20, v20
	v_fmac_f32_e32 v34, v16, v16
	v_add_f32_e32 v19, v19, v34
	v_add_f32_e32 v18, v19, v18
	ds_bpermute_b32 v19, v166, v18
	s_andn2_b64 vcc, exec, s[42:43]
	s_waitcnt lgkmcnt(0)
	v_add_f32_e32 v18, v18, v19
	ds_bpermute_b32 v19, v167, v18
	s_waitcnt lgkmcnt(0)
	v_add_f32_e32 v18, v18, v19
	ds_bpermute_b32 v19, v168, v18
	s_waitcnt lgkmcnt(0)
	v_add_f32_e32 v18, v18, v19
	ds_bpermute_b32 v19, v169, v18
	s_waitcnt lgkmcnt(0)
	v_add_f32_e32 v18, v18, v19
	ds_bpermute_b32 v19, v170, v18
	s_waitcnt lgkmcnt(0)
	v_add_f32_e32 v18, v18, v19
	ds_bpermute_b32 v19, v171, v18
	s_cbranch_vccnz .LBB0_3066
	s_waitcnt lgkmcnt(0)
	v_add_f32_e32 v18, v18, v19
	v_fmamk_f32 v18, v18, 0x3a800000, v165
	v_rsq_f32_e32 v18, v18
	s_lshl_b64 s[0:1], s[96:97], 12
	v_pk_mul_f32 v[34:35], v[32:33], v[18:19] op_sel_hi:[1,0]
	v_pk_mul_f32 v[30:31], v[30:31], v[18:19] op_sel_hi:[1,0]
	v_pk_mul_f32 v[26:27], v[26:27], v[18:19] op_sel_hi:[1,0]
	s_waitcnt vmcnt(2)
	v_pk_mul_f32 v[32:33], v[94:95], v[30:31]
	v_pk_mul_f32 v[30:31], v[92:93], v[34:35]
	v_lshl_add_u64 v[34:35], v[148:149], 0, s[0:1]
	global_store_dwordx4 v[34:35], v[30:33], off nt
	v_pk_mul_f32 v[22:23], v[22:23], v[18:19] op_sel_hi:[1,0]
	v_pk_mul_f32 v[20:21], v[20:21], v[18:19] op_sel_hi:[1,0]
	v_pk_mul_f32 v[30:31], v[28:29], v[18:19] op_sel_hi:[1,0]
	v_pk_mul_f32 v[28:29], v[90:91], v[26:27]
	v_pk_mul_f32 v[26:27], v[88:89], v[30:31]
	global_store_dwordx4 v[34:35], v[26:29], off offset:16 nt
	v_pk_mul_f32 v[16:17], v[16:17], v[18:19] op_sel_hi:[1,0]
	s_nop 0
	v_pk_mul_f32 v[26:27], v[24:25], v[18:19] op_sel_hi:[1,0]
	s_waitcnt vmcnt(2)
	v_pk_mul_f32 v[24:25], v[82:83], v[22:23]
	v_pk_mul_f32 v[22:23], v[80:81], v[26:27]
	v_pk_mul_f32 v[18:19], v[78:79], v[16:17]
	v_pk_mul_f32 v[16:17], v[76:77], v[20:21]
	global_store_dwordx4 v[34:35], v[22:25], off offset:2048 nt
	global_store_dwordx4 v[34:35], v[16:19], off offset:2064 nt
.LBB0_3066:
	s_nop 0
	v_and_b32_e32 v25, 0xffff0000, v12
	v_and_b32_e32 v23, 0xffff0000, v13
	v_lshlrev_b32_e32 v24, 16, v12
	v_lshlrev_b32_e32 v22, 16, v13
	v_lshlrev_b32_e32 v20, 16, v14
	v_and_b32_e32 v21, 0xffff0000, v14
	v_lshlrev_b32_e32 v18, 16, v15
	s_waitcnt lgkmcnt(0)
	v_and_b32_e32 v19, 0xffff0000, v15
	v_lshlrev_b32_e32 v16, 16, v8
	v_and_b32_e32 v17, 0xffff0000, v8
	v_lshlrev_b32_e32 v14, 16, v9
	v_and_b32_e32 v15, 0xffff0000, v9
	v_lshlrev_b32_e32 v12, 16, v10
	v_and_b32_e32 v13, 0xffff0000, v10
	v_lshlrev_b32_e32 v8, 16, v11
	v_and_b32_e32 v9, 0xffff0000, v11
	v_mul_f32_e32 v10, v25, v25
	v_mul_f32_e32 v11, v23, v23
	v_fmac_f32_e32 v10, v24, v24
	v_fmac_f32_e32 v11, v22, v22
	v_add_f32_e32 v10, v10, v11
	v_mul_f32_e32 v11, v21, v21
	v_mul_f32_e32 v26, v19, v19
	v_fmac_f32_e32 v11, v20, v20
	v_fmac_f32_e32 v26, v18, v18
	v_add_f32_e32 v11, v11, v26
	v_add_f32_e32 v10, v10, v11
	v_mul_f32_e32 v11, v17, v17
	v_mul_f32_e32 v26, v15, v15
	v_fmac_f32_e32 v11, v16, v16
	v_fmac_f32_e32 v26, v14, v14
	v_add_f32_e32 v11, v11, v26
	v_add_f32_e32 v10, v11, v10
	v_mul_f32_e32 v11, v13, v13
	v_mul_f32_e32 v26, v9, v9
	v_fmac_f32_e32 v11, v12, v12
	v_fmac_f32_e32 v26, v8, v8
	v_add_f32_e32 v11, v11, v26
	v_add_f32_e32 v10, v11, v10
	ds_bpermute_b32 v11, v166, v10
	s_andn2_b64 vcc, exec, s[40:41]
	s_waitcnt lgkmcnt(0)
	v_add_f32_e32 v10, v10, v11
	ds_bpermute_b32 v11, v167, v10
	s_waitcnt lgkmcnt(0)
	v_add_f32_e32 v10, v10, v11
	ds_bpermute_b32 v11, v168, v10
	s_waitcnt lgkmcnt(0)
	v_add_f32_e32 v10, v10, v11
	ds_bpermute_b32 v11, v169, v10
	s_waitcnt lgkmcnt(0)
	v_add_f32_e32 v10, v10, v11
	ds_bpermute_b32 v11, v170, v10
	s_waitcnt lgkmcnt(0)
	v_add_f32_e32 v10, v10, v11
	ds_bpermute_b32 v11, v171, v10
	s_cbranch_vccnz .LBB0_3068
	s_waitcnt lgkmcnt(0)
	v_add_f32_e32 v10, v10, v11
	v_fmamk_f32 v10, v10, 0x3a800000, v165
	v_rsq_f32_e32 v10, v10
	s_lshl_b64 s[0:1], s[94:95], 12
	v_pk_mul_f32 v[26:27], v[24:25], v[10:11] op_sel_hi:[1,0]
	v_pk_mul_f32 v[22:23], v[22:23], v[10:11] op_sel_hi:[1,0]
	v_pk_mul_f32 v[18:19], v[18:19], v[10:11] op_sel_hi:[1,0]
	s_waitcnt vmcnt(2)
	v_pk_mul_f32 v[24:25], v[94:95], v[22:23]
	v_pk_mul_f32 v[22:23], v[92:93], v[26:27]
	v_lshl_add_u64 v[26:27], v[148:149], 0, s[0:1]
	global_store_dwordx4 v[26:27], v[22:25], off nt
	v_pk_mul_f32 v[14:15], v[14:15], v[10:11] op_sel_hi:[1,0]
	v_pk_mul_f32 v[12:13], v[12:13], v[10:11] op_sel_hi:[1,0]
	v_pk_mul_f32 v[22:23], v[20:21], v[10:11] op_sel_hi:[1,0]
	v_pk_mul_f32 v[20:21], v[90:91], v[18:19]
	v_pk_mul_f32 v[18:19], v[88:89], v[22:23]
	global_store_dwordx4 v[26:27], v[18:21], off offset:16 nt
	v_pk_mul_f32 v[8:9], v[8:9], v[10:11] op_sel_hi:[1,0]
	s_nop 0
	v_pk_mul_f32 v[18:19], v[16:17], v[10:11] op_sel_hi:[1,0]
	s_waitcnt vmcnt(2)
	v_pk_mul_f32 v[16:17], v[82:83], v[14:15]
	v_pk_mul_f32 v[14:15], v[80:81], v[18:19]
	v_pk_mul_f32 v[10:11], v[78:79], v[8:9]
	v_pk_mul_f32 v[8:9], v[76:77], v[12:13]
	global_store_dwordx4 v[26:27], v[14:17], off offset:2048 nt
	global_store_dwordx4 v[26:27], v[8:11], off offset:2064 nt
.LBB0_3068:
	s_nop 0
	v_and_b32_e32 v17, 0xffff0000, v4
	v_and_b32_e32 v15, 0xffff0000, v5
	v_lshlrev_b32_e32 v16, 16, v4
	v_lshlrev_b32_e32 v14, 16, v5
	v_lshlrev_b32_e32 v12, 16, v6
	v_and_b32_e32 v13, 0xffff0000, v6
	v_lshlrev_b32_e32 v10, 16, v7
	s_waitcnt lgkmcnt(0)
	v_and_b32_e32 v11, 0xffff0000, v7
	v_lshlrev_b32_e32 v8, 16, v0
	v_and_b32_e32 v9, 0xffff0000, v0
	v_lshlrev_b32_e32 v6, 16, v1
	v_and_b32_e32 v7, 0xffff0000, v1
	v_lshlrev_b32_e32 v4, 16, v2
	v_and_b32_e32 v5, 0xffff0000, v2
	v_lshlrev_b32_e32 v0, 16, v3
	v_and_b32_e32 v1, 0xffff0000, v3
	v_mul_f32_e32 v2, v17, v17
	v_mul_f32_e32 v3, v15, v15
	v_fmac_f32_e32 v2, v16, v16
	v_fmac_f32_e32 v3, v14, v14
	v_add_f32_e32 v2, v2, v3
	v_mul_f32_e32 v3, v13, v13
	v_mul_f32_e32 v18, v11, v11
	v_fmac_f32_e32 v3, v12, v12
	v_fmac_f32_e32 v18, v10, v10
	v_add_f32_e32 v3, v3, v18
	v_add_f32_e32 v2, v2, v3
	v_mul_f32_e32 v3, v9, v9
	v_mul_f32_e32 v18, v7, v7
	v_fmac_f32_e32 v3, v8, v8
	v_fmac_f32_e32 v18, v6, v6
	v_add_f32_e32 v3, v3, v18
	v_add_f32_e32 v2, v3, v2
	v_mul_f32_e32 v3, v5, v5
	v_mul_f32_e32 v18, v1, v1
	v_fmac_f32_e32 v3, v4, v4
	v_fmac_f32_e32 v18, v0, v0
	v_add_f32_e32 v3, v3, v18
	v_add_f32_e32 v2, v3, v2
	ds_bpermute_b32 v3, v166, v2
	s_andn2_b64 vcc, exec, s[38:39]
	s_waitcnt lgkmcnt(0)
	v_add_f32_e32 v2, v2, v3
	ds_bpermute_b32 v3, v167, v2
	s_waitcnt lgkmcnt(0)
	v_add_f32_e32 v2, v2, v3
	ds_bpermute_b32 v3, v168, v2
	s_waitcnt lgkmcnt(0)
	v_add_f32_e32 v2, v2, v3
	ds_bpermute_b32 v3, v169, v2
	s_waitcnt lgkmcnt(0)
	v_add_f32_e32 v2, v2, v3
	ds_bpermute_b32 v3, v170, v2
	s_waitcnt lgkmcnt(0)
	v_add_f32_e32 v2, v2, v3
	ds_bpermute_b32 v3, v171, v2
	s_cbranch_vccnz .LBB0_3070
	s_waitcnt lgkmcnt(0)
	v_add_f32_e32 v2, v2, v3
	v_fmamk_f32 v2, v2, 0x3a800000, v165
	v_rsq_f32_e32 v2, v2
	s_lshl_b64 s[0:1], s[92:93], 12
	v_pk_mul_f32 v[18:19], v[16:17], v[2:3] op_sel_hi:[1,0]
	v_pk_mul_f32 v[14:15], v[14:15], v[2:3] op_sel_hi:[1,0]
	v_pk_mul_f32 v[10:11], v[10:11], v[2:3] op_sel_hi:[1,0]
	s_waitcnt vmcnt(2)
	v_pk_mul_f32 v[16:17], v[94:95], v[14:15]
	v_pk_mul_f32 v[14:15], v[92:93], v[18:19]
	v_lshl_add_u64 v[18:19], v[148:149], 0, s[0:1]
	global_store_dwordx4 v[18:19], v[14:17], off nt
	v_pk_mul_f32 v[6:7], v[6:7], v[2:3] op_sel_hi:[1,0]
	v_pk_mul_f32 v[4:5], v[4:5], v[2:3] op_sel_hi:[1,0]
	v_pk_mul_f32 v[14:15], v[12:13], v[2:3] op_sel_hi:[1,0]
	v_pk_mul_f32 v[12:13], v[90:91], v[10:11]
	v_pk_mul_f32 v[10:11], v[88:89], v[14:15]
	global_store_dwordx4 v[18:19], v[10:13], off offset:16 nt
	v_pk_mul_f32 v[0:1], v[0:1], v[2:3] op_sel_hi:[1,0]
	s_nop 0
	v_pk_mul_f32 v[10:11], v[8:9], v[2:3] op_sel_hi:[1,0]
	s_waitcnt vmcnt(2)
	v_pk_mul_f32 v[8:9], v[82:83], v[6:7]
	v_pk_mul_f32 v[6:7], v[80:81], v[10:11]
	v_pk_mul_f32 v[2:3], v[78:79], v[0:1]
	v_pk_mul_f32 v[0:1], v[76:77], v[4:5]
	global_store_dwordx4 v[18:19], v[6:9], off offset:2048 nt
	global_store_dwordx4 v[18:19], v[0:3], off offset:2064 nt
